# GEMM K-loop: uniform-branch ballots (v_cndmask+v_cmp) -> s_andn2, two-level flag dispatch before extra-row MFMAs -> single branch
# baseline (speedup 1.0000x reference)
; #define PG8_STAGE(bufoff, gbase, voff) do { _Pragma("unroll") for (int _i = 0; _i < 2; ++_i) glds16_s((voff)[_i], (const void*)(gbase), ldsbase + (unsigned)((bufoff) + _i * 8192) + ldsw); } while (0)
; #define PG8_STAGEX(pb, gbase) glds16_s(voffX, (const void*)(gbase), ldsbase + (unsigned)(XOFF + (pb) * 4096) + ldsx)
; #define PG8_LDA(dst, b, h) do { _Pragma("unroll") for (int m = 0; m < 4; ++m) _Pragma("unroll") for (int k = 0; k < 2; ++k) dst[m][k] = *(const PG8_LAS bf16x8*)(lds + PG8_SA(b, h) + aoff + m * 2048 + k * 1024); } while (0)
; #define PG8_LDB(dst, b, h) do { _Pragma("unroll") for (int n = 0; n < 2; ++n) _Pragma("unroll") for (int k = 0; k < 2; ++k) dst[n][k] = *(const PG8_LAS bf16x8*)(lds + PG8_SB(b, h) + boff + n * 2048 + k * 1024); } while (0)
; #define PG8_LDX(pb, tp) do { _Pragma("unroll") for (int k = 0; k < 2; ++k) Ax[k] = *(const PG8_LAS bf16x8*)(lds + xoff + (pb) * 4096 + (tp) * 128 + k * 64); } while (0)
; #define PG8_MMA(ai, bj, At, Bt) do { __builtin_amdgcn_s_setprio(1); _Pragma("unroll") for (int m = 0; m < 4; ++m) _Pragma("unroll") for (int n = 0; n < 2; ++n) _Pragma("unroll") for (int k = 0; k < 2; ++k) \
;         acc[ai][bj][m][n] = __builtin_amdgcn_mfma_f32_16x16x32_bf16(Bt[n][k], At[m][k], acc[ai][bj][m][n], 0, 0, 0); __builtin_amdgcn_s_setprio(0); } while (0)
; #define PG8_WAIT_V(n) asm volatile("s_waitcnt vmcnt(" #n ")" ::: "memory")
; template <class Epi, class Sched, bool HM = false>
; __device__ __forceinline__ void gemm_phase(PG8_LAS unsigned char* lds, const Gemm g, const Sched& S, const Epi& E) {
;     ...
;             const bool last = (t == nt - 2);
;             const char* a1 = cA + (size_t)(t + 1) * kstep;
;             const char* a2 = last ? nA : cA + (size_t)(t + 2) * kstep; const char* b2 = last ? nB : cB + (size_t)(t + 2) * kstep;
;             const char* a3 = a2 + kstep; const char* b3 = b2 + kstep;
;             asm volatile("; uniform bases" : "+s"(a1), "+s"(a2), "+s"(a3), "+s"(b2), "+s"(b3));
;             if (last && has_next) S.a_ready(nxt);
;             const int pb = (t >> 1) & 1;
;             PG8_LDB(B0, 0, 0); PG8_LDB(B1, 0, 1); PG8_SCHED; PG8_LDA(At, 0, 0); if (hasx) PG8_LDX(pb, 0); PG8_STAGE(PG8_SA(1, 1), a1 + hstepA, voffA); PG8_STAGEX(pb ^ 1, a2 + xstep);
;             PG8_WAIT_V(9); PG8_WAIT_L(0); PG8_BAR; PG8_MMA(0, 0, At, B0); PG8_MMA(0, 1, At, B1); if (hasx) PG8_MMAX(); PG8_BAR; PG8_SCHED;
.LBB0_256:
	s_add_u32 s34, s27, 0xffffff80
	s_addc_u32 s35, s39, -1
	s_cmp_eq_u32 s23, 4
	s_cselect_b32 s92, s84, s27
	s_cselect_b32 s93, s85, s39
	s_cselect_b32 s9, s91, s38
	s_cselect_b32 s8, s90, s95
	s_add_u32 s4, s92, 0x80
	s_addc_u32 s5, s93, 0
	s_add_u32 s6, s8, 0x80
	s_addc_u32 s7, s9, 0
	v_add_u32_e32 v2, 0x10000, v234
	ds_read_b128 v[166:169], v2
	ds_read_b128 v[170:173], v2 offset:1024
	ds_read_b128 v[174:177], v2 offset:2048
	ds_read_b128 v[178:181], v2 offset:3072
	v_add_u32_e32 v2, 0x14000, v234
	ds_read_b128 v[150:153], v2
	ds_read_b128 v[154:157], v2 offset:1024
	ds_read_b128 v[158:161], v2 offset:2048
	s_waitcnt lgkmcnt(7)
	ds_read_b128 v[162:165], v2 offset:3072
	ds_read_b128 v[206:209], v235
	ds_read_b128 v[210:213], v235 offset:1024
	ds_read_b128 v[198:201], v235 offset:2048
	ds_read_b128 v[202:205], v235 offset:3072
	ds_read_b128 v[190:193], v235 offset:4096
	ds_read_b128 v[194:197], v235 offset:5120
	ds_read_b128 v[182:185], v235 offset:6144
	ds_read_b128 v[186:189], v235 offset:7168
	s_and_b32 s20, s22, 0x1000
	s_andn2_b64 s[42:43], exec, s[62:63]
	s_andn2_b64 vcc, exec, s[62:63]
	v_add_u32_e32 v2, s20, v232
	s_cbranch_vccnz .LBB0_258
	ds_read_b128 v[6:9], v2
	v_xor_b32_e32 v10, 64, v2
	ds_read_b128 v[10:13], v10
.LBB0_258:
	s_add_u32 s34, s34, 0x80000
	s_addc_u32 s35, s35, 0
	s_mov_b32 s21, m0
	s_mov_b32 m0, s59
	s_nop 0
	global_load_lds_dwordx4 v225, s[34:35]
	s_mov_b32 m0, s21
	s_nop 0
	s_mov_b32 s21, m0
	s_mov_b32 m0, s83
	s_nop 0
	global_load_lds_dwordx4 v227, s[34:35]
	s_mov_b32 m0, s21
	s_add_u32 s34, s92, 0x100000
	s_addc_u32 s35, s93, 0
	s_xor_b32 s20, s20, 0x21400
	s_add_i32 s20, s29, s20
	s_mov_b32 s21, m0
	s_mov_b32 m0, s20
	s_nop 0
	global_load_lds_dwordx4 v229, s[34:35]
	s_mov_b32 m0, s21
	s_waitcnt vmcnt(9)
	s_waitcnt lgkmcnt(0)
	s_barrier
	s_setprio 1
	s_waitcnt lgkmcnt(7)
	v_mfma_f32_16x16x32_bf16 v[146:149], v[166:169], v[206:209], v[146:149]
	v_mfma_f32_16x16x32_bf16 v[142:145], v[174:177], v[206:209], v[142:145]
	s_waitcnt lgkmcnt(5)
	v_mfma_f32_16x16x32_bf16 v[138:141], v[166:169], v[198:201], v[138:141]
	v_mfma_f32_16x16x32_bf16 v[130:133], v[174:177], v[198:201], v[130:133]
	s_waitcnt lgkmcnt(3)
	v_mfma_f32_16x16x32_bf16 v[122:125], v[166:169], v[190:193], v[122:125]
	v_mfma_f32_16x16x32_bf16 v[114:117], v[174:177], v[190:193], v[114:117]
	s_waitcnt lgkmcnt(1)
	v_mfma_f32_16x16x32_bf16 v[106:109], v[166:169], v[182:185], v[106:109]
	v_mfma_f32_16x16x32_bf16 v[98:101], v[174:177], v[182:185], v[98:101]
	v_mfma_f32_16x16x32_bf16 v[146:149], v[170:173], v[210:213], v[146:149]
	v_mfma_f32_16x16x32_bf16 v[142:145], v[178:181], v[210:213], v[142:145]
	v_mfma_f32_16x16x32_bf16 v[138:141], v[170:173], v[202:205], v[138:141]
	v_mfma_f32_16x16x32_bf16 v[130:133], v[178:181], v[202:205], v[130:133]
	v_mfma_f32_16x16x32_bf16 v[122:125], v[170:173], v[194:197], v[122:125]
	v_mfma_f32_16x16x32_bf16 v[114:117], v[178:181], v[194:197], v[114:117]
	s_waitcnt lgkmcnt(0)
	v_mfma_f32_16x16x32_bf16 v[106:109], v[170:173], v[186:189], v[106:109]
	v_mfma_f32_16x16x32_bf16 v[98:101], v[178:181], v[186:189], v[98:101]
	s_setprio 0
	s_setprio 1
	v_mfma_f32_16x16x32_bf16 v[134:137], v[150:153], v[206:209], v[134:137]
	v_mfma_f32_16x16x32_bf16 v[126:129], v[158:161], v[206:209], v[126:129]
	v_mfma_f32_16x16x32_bf16 v[118:121], v[150:153], v[198:201], v[118:121]
	v_mfma_f32_16x16x32_bf16 v[110:113], v[158:161], v[198:201], v[110:113]
	v_mfma_f32_16x16x32_bf16 v[102:105], v[150:153], v[190:193], v[102:105]
	v_mfma_f32_16x16x32_bf16 v[94:97], v[158:161], v[190:193], v[94:97]
	v_mfma_f32_16x16x32_bf16 v[90:93], v[150:153], v[182:185], v[90:93]
	v_mfma_f32_16x16x32_bf16 v[86:89], v[158:161], v[182:185], v[86:89]
	v_mfma_f32_16x16x32_bf16 v[134:137], v[154:157], v[210:213], v[134:137]
	v_mfma_f32_16x16x32_bf16 v[126:129], v[162:165], v[210:213], v[126:129]
	v_mfma_f32_16x16x32_bf16 v[118:121], v[154:157], v[202:205], v[118:121]
	v_mfma_f32_16x16x32_bf16 v[110:113], v[162:165], v[202:205], v[110:113]
	v_mfma_f32_16x16x32_bf16 v[102:105], v[154:157], v[194:197], v[102:105]
	v_mfma_f32_16x16x32_bf16 v[94:97], v[162:165], v[194:197], v[94:97]
	v_mfma_f32_16x16x32_bf16 v[90:93], v[154:157], v[186:189], v[90:93]
	v_mfma_f32_16x16x32_bf16 v[86:89], v[162:165], v[186:189], v[86:89]
	s_setprio 0
	s_andn2_b64 s[44:45], exec, s[76:77]
	s_and_b64 vcc, exec, s[42:43]
	s_cbranch_vccnz .LBB0_264
	s_and_b64 vcc, exec, s[44:45]
	s_cbranch_vccnz .LBB0_261
	v_mfma_f32_16x16x32_bf16 v[18:21], v[174:177], v[6:9], v[18:21]
	v_mfma_f32_16x16x32_bf16 v[14:17], v[158:161], v[6:9], v[14:17]
	v_mfma_f32_16x16x32_bf16 v[18:21], v[178:181], v[10:13], v[18:21]
	v_mfma_f32_16x16x32_bf16 v[14:17], v[162:165], v[10:13], v[14:17]
	s_branch .LBB0_264
.LBB0_261:
	v_mfma_f32_16x16x32_bf16 v[18:21], v[166:169], v[6:9], v[18:21]
	v_mfma_f32_16x16x32_bf16 v[14:17], v[150:153], v[6:9], v[14:17]
	v_mfma_f32_16x16x32_bf16 v[18:21], v[170:173], v[10:13], v[18:21]
	v_mfma_f32_16x16x32_bf16 v[14:17], v[154:157], v[10:13], v[14:17]

; #define PG8_STAGE(bufoff, gbase, voff) do { _Pragma("unroll") for (int _i = 0; _i < 2; ++_i) glds16_s((voff)[_i], (const void*)(gbase), ldsbase + (unsigned)((bufoff) + _i * 8192) + ldsw); } while (0)
; #define PG8_LDA(dst, b, h) do { _Pragma("unroll") for (int m = 0; m < 4; ++m) _Pragma("unroll") for (int k = 0; k < 2; ++k) dst[m][k] = *(const PG8_LAS bf16x8*)(lds + PG8_SA(b, h) + aoff + m * 2048 + k * 1024); } while (0)
; #define PG8_LDB(dst, b, h) do { _Pragma("unroll") for (int n = 0; n < 2; ++n) _Pragma("unroll") for (int k = 0; k < 2; ++k) dst[n][k] = *(const PG8_LAS bf16x8*)(lds + PG8_SB(b, h) + boff + n * 2048 + k * 1024); } while (0)
; #define PG8_LDX(pb, tp) do { _Pragma("unroll") for (int k = 0; k < 2; ++k) Ax[k] = *(const PG8_LAS bf16x8*)(lds + xoff + (pb) * 4096 + (tp) * 128 + k * 64); } while (0)
; #define PG8_MMA(ai, bj, At, Bt) do { __builtin_amdgcn_s_setprio(1); _Pragma("unroll") for (int m = 0; m < 4; ++m) _Pragma("unroll") for (int n = 0; n < 2; ++n) _Pragma("unroll") for (int k = 0; k < 2; ++k) \
;         acc[ai][bj][m][n] = __builtin_amdgcn_mfma_f32_16x16x32_bf16(Bt[n][k], At[m][k], acc[ai][bj][m][n], 0, 0, 0); __builtin_amdgcn_s_setprio(0); } while (0)
; #define PG8_WAIT_V(n) asm volatile("s_waitcnt vmcnt(" #n ")" ::: "memory")
; #define PG8_WAIT_L(n) asm volatile("s_waitcnt lgkmcnt(" #n ")" ::: "memory")
; #define PG8_BAR __builtin_amdgcn_s_barrier()
; #define PG8_SCHED __builtin_amdgcn_sched_barrier(0)
; template <class Epi, class Sched, bool HM = false>
; __device__ __forceinline__ void gemm_phase(PG8_LAS unsigned char* lds, const Gemm g, const Sched& S, const Epi& E) {
;     ...
;             PG8_LDB(B0, 1, 0); PG8_LDB(B1, 1, 1); PG8_SCHED; PG8_LDA(At, 1, 0); if (hasx) PG8_LDX(pb, 1); PG8_STAGE(PG8_SA(0, 1), a2 + hstepA, voffA);
;             PG8_WAIT_V(9); PG8_WAIT_L(0); PG8_BAR; PG8_MMA(0, 0, At, B0); PG8_MMA(0, 1, At, B1); if (hasx) PG8_MMAX(); PG8_BAR; PG8_SCHED;
.LBB0_266:
	s_add_u32 s8, s92, 0x80000
	s_addc_u32 s9, s93, 0
	s_mov_b32 s20, m0
	s_mov_b32 m0, s30
	s_nop 0
	global_load_lds_dwordx4 v225, s[8:9]
	s_mov_b32 m0, s20
	s_nop 0
	s_mov_b32 s20, m0
	s_mov_b32 m0, s31
	s_nop 0
	global_load_lds_dwordx4 v227, s[8:9]
	s_mov_b32 m0, s20
	s_waitcnt vmcnt(9)
	s_waitcnt lgkmcnt(0)
	s_barrier
	s_setprio 1
	s_waitcnt lgkmcnt(7)
	v_mfma_f32_16x16x32_bf16 v[146:149], v[166:169], v[206:209], v[146:149]
	v_mfma_f32_16x16x32_bf16 v[142:145], v[174:177], v[206:209], v[142:145]
	s_waitcnt lgkmcnt(5)
	v_mfma_f32_16x16x32_bf16 v[138:141], v[166:169], v[198:201], v[138:141]
	v_mfma_f32_16x16x32_bf16 v[130:133], v[174:177], v[198:201], v[130:133]
	s_waitcnt lgkmcnt(3)
	v_mfma_f32_16x16x32_bf16 v[122:125], v[166:169], v[190:193], v[122:125]
	v_mfma_f32_16x16x32_bf16 v[114:117], v[174:177], v[190:193], v[114:117]
	s_waitcnt lgkmcnt(1)
	v_mfma_f32_16x16x32_bf16 v[106:109], v[166:169], v[182:185], v[106:109]
	v_mfma_f32_16x16x32_bf16 v[98:101], v[174:177], v[182:185], v[98:101]
	v_mfma_f32_16x16x32_bf16 v[146:149], v[170:173], v[210:213], v[146:149]
	v_mfma_f32_16x16x32_bf16 v[142:145], v[178:181], v[210:213], v[142:145]
	v_mfma_f32_16x16x32_bf16 v[138:141], v[170:173], v[202:205], v[138:141]
	v_mfma_f32_16x16x32_bf16 v[130:133], v[178:181], v[202:205], v[130:133]
	v_mfma_f32_16x16x32_bf16 v[122:125], v[170:173], v[194:197], v[122:125]
	v_mfma_f32_16x16x32_bf16 v[114:117], v[178:181], v[194:197], v[114:117]
	s_waitcnt lgkmcnt(0)
	v_mfma_f32_16x16x32_bf16 v[106:109], v[170:173], v[186:189], v[106:109]
	v_mfma_f32_16x16x32_bf16 v[98:101], v[178:181], v[186:189], v[98:101]
	s_setprio 0
	s_setprio 1
	v_mfma_f32_16x16x32_bf16 v[134:137], v[150:153], v[206:209], v[134:137]
	v_mfma_f32_16x16x32_bf16 v[126:129], v[158:161], v[206:209], v[126:129]
	v_mfma_f32_16x16x32_bf16 v[118:121], v[150:153], v[198:201], v[118:121]
	v_mfma_f32_16x16x32_bf16 v[110:113], v[158:161], v[198:201], v[110:113]
	v_mfma_f32_16x16x32_bf16 v[102:105], v[150:153], v[190:193], v[102:105]
	v_mfma_f32_16x16x32_bf16 v[94:97], v[158:161], v[190:193], v[94:97]
	v_mfma_f32_16x16x32_bf16 v[90:93], v[150:153], v[182:185], v[90:93]
	v_mfma_f32_16x16x32_bf16 v[86:89], v[158:161], v[182:185], v[86:89]
	v_mfma_f32_16x16x32_bf16 v[134:137], v[154:157], v[210:213], v[134:137]
	v_mfma_f32_16x16x32_bf16 v[126:129], v[162:165], v[210:213], v[126:129]
	v_mfma_f32_16x16x32_bf16 v[118:121], v[154:157], v[202:205], v[118:121]
	v_mfma_f32_16x16x32_bf16 v[110:113], v[162:165], v[202:205], v[110:113]
	v_mfma_f32_16x16x32_bf16 v[102:105], v[154:157], v[194:197], v[102:105]
	v_mfma_f32_16x16x32_bf16 v[94:97], v[162:165], v[194:197], v[94:97]
	v_mfma_f32_16x16x32_bf16 v[90:93], v[154:157], v[186:189], v[90:93]
	v_mfma_f32_16x16x32_bf16 v[86:89], v[162:165], v[186:189], v[86:89]
	s_setprio 0
	s_and_b64 vcc, exec, s[42:43]
	s_cbranch_vccnz .LBB0_255
	s_and_b64 vcc, exec, s[44:45]
	s_cbranch_vccnz .LBB0_269
	v_mfma_f32_16x16x32_bf16 v[18:21], v[174:177], v[6:9], v[18:21]
	v_mfma_f32_16x16x32_bf16 v[14:17], v[158:161], v[6:9], v[14:17]
	v_mfma_f32_16x16x32_bf16 v[18:21], v[178:181], v[10:13], v[18:21]
	v_mfma_f32_16x16x32_bf16 v[14:17], v[162:165], v[10:13], v[14:17]
	s_branch .LBB0_254
.LBB0_269:
	v_mfma_f32_16x16x32_bf16 v[18:21], v[166:169], v[6:9], v[18:21]
	v_mfma_f32_16x16x32_bf16 v[14:17], v[150:153], v[6:9], v[14:17]
	v_mfma_f32_16x16x32_bf16 v[18:21], v[170:173], v[10:13], v[18:21]
	v_mfma_f32_16x16x32_bf16 v[14:17], v[154:157], v[10:13], v[14:17]
	s_branch .LBB0_254

; #define PG8_STAGE(bufoff, gbase, voff) do { _Pragma("unroll") for (int _i = 0; _i < 2; ++_i) glds16_s((voff)[_i], (const void*)(gbase), ldsbase + (unsigned)((bufoff) + _i * 8192) + ldsw); } while (0)
; #define PG8_STAGEX(pb, gbase) glds16_s(voffX, (const void*)(gbase), ldsbase + (unsigned)(XOFF + (pb) * 4096) + ldsx)
; #define PG8_LDA(dst, b, h) do { _Pragma("unroll") for (int m = 0; m < 4; ++m) _Pragma("unroll") for (int k = 0; k < 2; ++k) dst[m][k] = *(const PG8_LAS bf16x8*)(lds + PG8_SA(b, h) + aoff + m * 2048 + k * 1024); } while (0)
; #define PG8_LDB(dst, b, h) do { _Pragma("unroll") for (int n = 0; n < 2; ++n) _Pragma("unroll") for (int k = 0; k < 2; ++k) dst[n][k] = *(const PG8_LAS bf16x8*)(lds + PG8_SB(b, h) + boff + n * 2048 + k * 1024); } while (0)
; #define PG8_LDX(pb, tp) do { _Pragma("unroll") for (int k = 0; k < 2; ++k) Ax[k] = *(const PG8_LAS bf16x8*)(lds + xoff + (pb) * 4096 + (tp) * 128 + k * 64); } while (0)
; #define PG8_MMA(ai, bj, At, Bt) do { __builtin_amdgcn_s_setprio(1); _Pragma("unroll") for (int m = 0; m < 4; ++m) _Pragma("unroll") for (int n = 0; n < 2; ++n) _Pragma("unroll") for (int k = 0; k < 2; ++k) \
;         acc[ai][bj][m][n] = __builtin_amdgcn_mfma_f32_16x16x32_bf16(Bt[n][k], At[m][k], acc[ai][bj][m][n], 0, 0, 0); __builtin_amdgcn_s_setprio(0); } while (0)
; #define PG8_WAIT_V(n) asm volatile("s_waitcnt vmcnt(" #n ")" ::: "memory")
; template <class Epi, class Sched, bool HM = false>
; __device__ __forceinline__ void gemm_phase(PG8_LAS unsigned char* lds, const Gemm g, const Sched& S, const Epi& E) {
;     ...
;             const bool last = (t == nt - 2);
;             const char* a1 = cA + (size_t)(t + 1) * kstep;
;             const char* a2 = last ? nA : cA + (size_t)(t + 2) * kstep; const char* b2 = last ? nB : cB + (size_t)(t + 2) * kstep;
;             const char* a3 = a2 + kstep; const char* b3 = b2 + kstep;
;             asm volatile("; uniform bases" : "+s"(a1), "+s"(a2), "+s"(a3), "+s"(b2), "+s"(b3));
;             if (last && has_next) S.a_ready(nxt);
;             const int pb = (t >> 1) & 1;
;             PG8_LDB(B0, 0, 0); PG8_LDB(B1, 0, 1); PG8_SCHED; PG8_LDA(At, 0, 0); if (hasx) PG8_LDX(pb, 0); PG8_STAGE(PG8_SA(1, 1), a1 + hstepA, voffA); PG8_STAGEX(pb ^ 1, a2 + xstep);
;             PG8_WAIT_V(9); PG8_WAIT_L(0); PG8_BAR; PG8_MMA(0, 0, At, B0); PG8_MMA(0, 1, At, B1); if (hasx) PG8_MMAX(); PG8_BAR; PG8_SCHED;
.LBB0_534:
	s_add_u32 s34, s27, 0xffffff80
	s_addc_u32 s35, s82, -1
	s_cmp_eq_u32 s23, 28
	s_cselect_b32 s94, s90, s27
	s_cselect_b32 s95, s91, s82
	s_cselect_b32 s9, s93, s39
	s_cselect_b32 s8, s92, s38
	s_add_u32 s4, s94, 0x80
	s_addc_u32 s5, s95, 0
	s_add_u32 s6, s8, 0x80
	s_addc_u32 s7, s9, 0
	v_add_u32_e32 v2, 0x10000, v234
	ds_read_b128 v[166:169], v2
	ds_read_b128 v[170:173], v2 offset:1024
	ds_read_b128 v[174:177], v2 offset:2048
	ds_read_b128 v[178:181], v2 offset:3072
	v_add_u32_e32 v2, 0x14000, v234
	ds_read_b128 v[150:153], v2
	ds_read_b128 v[154:157], v2 offset:1024
	ds_read_b128 v[158:161], v2 offset:2048
	s_waitcnt lgkmcnt(7)
	ds_read_b128 v[162:165], v2 offset:3072
	ds_read_b128 v[206:209], v235
	ds_read_b128 v[210:213], v235 offset:1024
	ds_read_b128 v[198:201], v235 offset:2048
	ds_read_b128 v[202:205], v235 offset:3072
	ds_read_b128 v[190:193], v235 offset:4096
	ds_read_b128 v[194:197], v235 offset:5120
	ds_read_b128 v[182:185], v235 offset:6144
	ds_read_b128 v[186:189], v235 offset:7168
	s_and_b32 s20, s22, 0x1000
	s_andn2_b64 s[42:43], exec, s[54:55]
	s_andn2_b64 vcc, exec, s[54:55]
	v_add_u32_e32 v2, s20, v232
	s_cbranch_vccnz .LBB0_536
	ds_read_b128 v[6:9], v2
	v_xor_b32_e32 v10, 64, v2
	ds_read_b128 v[10:13], v10
.LBB0_536:
	s_add_u32 s34, s34, 0x80000
	s_addc_u32 s35, s35, 0
	s_mov_b32 s21, m0
	s_mov_b32 m0, s83
	s_nop 0
	global_load_lds_dwordx4 v225, s[34:35]
	s_mov_b32 m0, s21
	s_nop 0
	s_mov_b32 s21, m0
	s_mov_b32 m0, s88
	s_nop 0
	global_load_lds_dwordx4 v227, s[34:35]
	s_mov_b32 m0, s21
	s_add_u32 s34, s94, 0x100000
	s_addc_u32 s35, s95, 0
	s_xor_b32 s20, s20, 0x21400
	s_add_i32 s20, s30, s20
	s_mov_b32 s21, m0
	s_mov_b32 m0, s20
	s_nop 0
	global_load_lds_dwordx4 v229, s[34:35]
	s_mov_b32 m0, s21
	s_waitcnt vmcnt(9)
	s_waitcnt lgkmcnt(0)
	s_barrier
	s_setprio 1
	s_waitcnt lgkmcnt(7)
	v_mfma_f32_16x16x32_bf16 v[146:149], v[166:169], v[206:209], v[146:149]
	v_mfma_f32_16x16x32_bf16 v[142:145], v[174:177], v[206:209], v[142:145]
	s_waitcnt lgkmcnt(5)
	v_mfma_f32_16x16x32_bf16 v[138:141], v[166:169], v[198:201], v[138:141]
	v_mfma_f32_16x16x32_bf16 v[130:133], v[174:177], v[198:201], v[130:133]
	s_waitcnt lgkmcnt(3)
	v_mfma_f32_16x16x32_bf16 v[122:125], v[166:169], v[190:193], v[122:125]
	v_mfma_f32_16x16x32_bf16 v[114:117], v[174:177], v[190:193], v[114:117]
	s_waitcnt lgkmcnt(1)
	v_mfma_f32_16x16x32_bf16 v[106:109], v[166:169], v[182:185], v[106:109]
	v_mfma_f32_16x16x32_bf16 v[98:101], v[174:177], v[182:185], v[98:101]
	v_mfma_f32_16x16x32_bf16 v[146:149], v[170:173], v[210:213], v[146:149]
	v_mfma_f32_16x16x32_bf16 v[142:145], v[178:181], v[210:213], v[142:145]
	v_mfma_f32_16x16x32_bf16 v[138:141], v[170:173], v[202:205], v[138:141]
	v_mfma_f32_16x16x32_bf16 v[130:133], v[178:181], v[202:205], v[130:133]
	v_mfma_f32_16x16x32_bf16 v[122:125], v[170:173], v[194:197], v[122:125]
	v_mfma_f32_16x16x32_bf16 v[114:117], v[178:181], v[194:197], v[114:117]
	s_waitcnt lgkmcnt(0)
	v_mfma_f32_16x16x32_bf16 v[106:109], v[170:173], v[186:189], v[106:109]
	v_mfma_f32_16x16x32_bf16 v[98:101], v[178:181], v[186:189], v[98:101]
	s_setprio 0
	s_setprio 1
	v_mfma_f32_16x16x32_bf16 v[134:137], v[150:153], v[206:209], v[134:137]
	v_mfma_f32_16x16x32_bf16 v[126:129], v[158:161], v[206:209], v[126:129]
	v_mfma_f32_16x16x32_bf16 v[118:121], v[150:153], v[198:201], v[118:121]
	v_mfma_f32_16x16x32_bf16 v[110:113], v[158:161], v[198:201], v[110:113]
	v_mfma_f32_16x16x32_bf16 v[102:105], v[150:153], v[190:193], v[102:105]
	v_mfma_f32_16x16x32_bf16 v[94:97], v[158:161], v[190:193], v[94:97]
	v_mfma_f32_16x16x32_bf16 v[90:93], v[150:153], v[182:185], v[90:93]
	v_mfma_f32_16x16x32_bf16 v[86:89], v[158:161], v[182:185], v[86:89]
	v_mfma_f32_16x16x32_bf16 v[134:137], v[154:157], v[210:213], v[134:137]
	v_mfma_f32_16x16x32_bf16 v[126:129], v[162:165], v[210:213], v[126:129]
	v_mfma_f32_16x16x32_bf16 v[118:121], v[154:157], v[202:205], v[118:121]
	v_mfma_f32_16x16x32_bf16 v[110:113], v[162:165], v[202:205], v[110:113]
	v_mfma_f32_16x16x32_bf16 v[102:105], v[154:157], v[194:197], v[102:105]
	v_mfma_f32_16x16x32_bf16 v[94:97], v[162:165], v[194:197], v[94:97]
	v_mfma_f32_16x16x32_bf16 v[90:93], v[154:157], v[186:189], v[90:93]
	v_mfma_f32_16x16x32_bf16 v[86:89], v[162:165], v[186:189], v[86:89]
	s_setprio 0
	s_andn2_b64 s[44:45], exec, s[78:79]
	s_and_b64 vcc, exec, s[42:43]
	s_cbranch_vccnz .LBB0_542
	s_and_b64 vcc, exec, s[44:45]
	s_cbranch_vccnz .LBB0_539
	v_mfma_f32_16x16x32_bf16 v[18:21], v[174:177], v[6:9], v[18:21]
	v_mfma_f32_16x16x32_bf16 v[14:17], v[158:161], v[6:9], v[14:17]
	v_mfma_f32_16x16x32_bf16 v[18:21], v[178:181], v[10:13], v[18:21]
	v_mfma_f32_16x16x32_bf16 v[14:17], v[162:165], v[10:13], v[14:17]
	s_branch .LBB0_542

; #define PG8_STAGE(bufoff, gbase, voff) do { _Pragma("unroll") for (int _i = 0; _i < 2; ++_i) glds16_s((voff)[_i], (const void*)(gbase), ldsbase + (unsigned)((bufoff) + _i * 8192) + ldsw); } while (0)
; #define PG8_LDA(dst, b, h) do { _Pragma("unroll") for (int m = 0; m < 4; ++m) _Pragma("unroll") for (int k = 0; k < 2; ++k) dst[m][k] = *(const PG8_LAS bf16x8*)(lds + PG8_SA(b, h) + aoff + m * 2048 + k * 1024); } while (0)
; #define PG8_LDB(dst, b, h) do { _Pragma("unroll") for (int n = 0; n < 2; ++n) _Pragma("unroll") for (int k = 0; k < 2; ++k) dst[n][k] = *(const PG8_LAS bf16x8*)(lds + PG8_SB(b, h) + boff + n * 2048 + k * 1024); } while (0)
; #define PG8_LDX(pb, tp) do { _Pragma("unroll") for (int k = 0; k < 2; ++k) Ax[k] = *(const PG8_LAS bf16x8*)(lds + xoff + (pb) * 4096 + (tp) * 128 + k * 64); } while (0)
; #define PG8_MMA(ai, bj, At, Bt) do { __builtin_amdgcn_s_setprio(1); _Pragma("unroll") for (int m = 0; m < 4; ++m) _Pragma("unroll") for (int n = 0; n < 2; ++n) _Pragma("unroll") for (int k = 0; k < 2; ++k) \
;         acc[ai][bj][m][n] = __builtin_amdgcn_mfma_f32_16x16x32_bf16(Bt[n][k], At[m][k], acc[ai][bj][m][n], 0, 0, 0); __builtin_amdgcn_s_setprio(0); } while (0)
; #define PG8_WAIT_V(n) asm volatile("s_waitcnt vmcnt(" #n ")" ::: "memory")
; #define PG8_WAIT_L(n) asm volatile("s_waitcnt lgkmcnt(" #n ")" ::: "memory")
; #define PG8_BAR __builtin_amdgcn_s_barrier()
; #define PG8_SCHED __builtin_amdgcn_sched_barrier(0)
; template <class Epi, class Sched, bool HM = false>
; __device__ __forceinline__ void gemm_phase(PG8_LAS unsigned char* lds, const Gemm g, const Sched& S, const Epi& E) {
;     ...
;             PG8_LDB(B0, 1, 0); PG8_LDB(B1, 1, 1); PG8_SCHED; PG8_LDA(At, 1, 0); if (hasx) PG8_LDX(pb, 1); PG8_STAGE(PG8_SA(0, 1), a2 + hstepA, voffA);
;             PG8_WAIT_V(9); PG8_WAIT_L(0); PG8_BAR; PG8_MMA(0, 0, At, B0); PG8_MMA(0, 1, At, B1); if (hasx) PG8_MMAX(); PG8_BAR; PG8_SCHED;
.LBB0_544:
	s_add_u32 s8, s94, 0x80000
	s_addc_u32 s9, s95, 0
	s_mov_b32 s20, m0
	s_mov_b32 m0, s31
	s_nop 0
	global_load_lds_dwordx4 v225, s[8:9]
	s_mov_b32 m0, s20
	s_nop 0
	s_mov_b32 s20, m0
	s_mov_b32 m0, s36
	s_nop 0
	global_load_lds_dwordx4 v227, s[8:9]
	s_mov_b32 m0, s20
	s_waitcnt vmcnt(9)
	s_waitcnt lgkmcnt(0)
	s_barrier
	s_setprio 1
	s_waitcnt lgkmcnt(7)
	v_mfma_f32_16x16x32_bf16 v[146:149], v[166:169], v[206:209], v[146:149]
	v_mfma_f32_16x16x32_bf16 v[142:145], v[174:177], v[206:209], v[142:145]
	s_waitcnt lgkmcnt(5)
	v_mfma_f32_16x16x32_bf16 v[138:141], v[166:169], v[198:201], v[138:141]
	v_mfma_f32_16x16x32_bf16 v[130:133], v[174:177], v[198:201], v[130:133]
	s_waitcnt lgkmcnt(3)
	v_mfma_f32_16x16x32_bf16 v[122:125], v[166:169], v[190:193], v[122:125]
	v_mfma_f32_16x16x32_bf16 v[114:117], v[174:177], v[190:193], v[114:117]
	s_waitcnt lgkmcnt(1)
	v_mfma_f32_16x16x32_bf16 v[106:109], v[166:169], v[182:185], v[106:109]
	v_mfma_f32_16x16x32_bf16 v[98:101], v[174:177], v[182:185], v[98:101]
	v_mfma_f32_16x16x32_bf16 v[146:149], v[170:173], v[210:213], v[146:149]
	v_mfma_f32_16x16x32_bf16 v[142:145], v[178:181], v[210:213], v[142:145]
	v_mfma_f32_16x16x32_bf16 v[138:141], v[170:173], v[202:205], v[138:141]
	v_mfma_f32_16x16x32_bf16 v[130:133], v[178:181], v[202:205], v[130:133]
	v_mfma_f32_16x16x32_bf16 v[122:125], v[170:173], v[194:197], v[122:125]
	v_mfma_f32_16x16x32_bf16 v[114:117], v[178:181], v[194:197], v[114:117]
	s_waitcnt lgkmcnt(0)
	v_mfma_f32_16x16x32_bf16 v[106:109], v[170:173], v[186:189], v[106:109]
	v_mfma_f32_16x16x32_bf16 v[98:101], v[178:181], v[186:189], v[98:101]
	s_setprio 0
	s_setprio 1
	v_mfma_f32_16x16x32_bf16 v[134:137], v[150:153], v[206:209], v[134:137]
	v_mfma_f32_16x16x32_bf16 v[126:129], v[158:161], v[206:209], v[126:129]
	v_mfma_f32_16x16x32_bf16 v[118:121], v[150:153], v[198:201], v[118:121]
	v_mfma_f32_16x16x32_bf16 v[110:113], v[158:161], v[198:201], v[110:113]
	v_mfma_f32_16x16x32_bf16 v[102:105], v[150:153], v[190:193], v[102:105]
	v_mfma_f32_16x16x32_bf16 v[94:97], v[158:161], v[190:193], v[94:97]
	v_mfma_f32_16x16x32_bf16 v[90:93], v[150:153], v[182:185], v[90:93]
	v_mfma_f32_16x16x32_bf16 v[86:89], v[158:161], v[182:185], v[86:89]
	v_mfma_f32_16x16x32_bf16 v[134:137], v[154:157], v[210:213], v[134:137]
	v_mfma_f32_16x16x32_bf16 v[126:129], v[162:165], v[210:213], v[126:129]
	v_mfma_f32_16x16x32_bf16 v[118:121], v[154:157], v[202:205], v[118:121]
	v_mfma_f32_16x16x32_bf16 v[110:113], v[162:165], v[202:205], v[110:113]
	v_mfma_f32_16x16x32_bf16 v[102:105], v[154:157], v[194:197], v[102:105]
	v_mfma_f32_16x16x32_bf16 v[94:97], v[162:165], v[194:197], v[94:97]
	v_mfma_f32_16x16x32_bf16 v[90:93], v[154:157], v[186:189], v[90:93]
	v_mfma_f32_16x16x32_bf16 v[86:89], v[162:165], v[186:189], v[86:89]
	s_setprio 0
	s_and_b64 vcc, exec, s[42:43]
	s_cbranch_vccnz .LBB0_533
	s_and_b64 vcc, exec, s[44:45]
	s_cbranch_vccnz .LBB0_547
	v_mfma_f32_16x16x32_bf16 v[18:21], v[174:177], v[6:9], v[18:21]
	v_mfma_f32_16x16x32_bf16 v[14:17], v[158:161], v[6:9], v[14:17]
	v_mfma_f32_16x16x32_bf16 v[18:21], v[178:181], v[10:13], v[18:21]
	v_mfma_f32_16x16x32_bf16 v[14:17], v[162:165], v[10:13], v[14:17]
	s_branch .LBB0_532

; #define PG8_STAGE(bufoff, gbase, voff) do { _Pragma("unroll") for (int _i = 0; _i < 2; ++_i) glds16_s((voff)[_i], (const void*)(gbase), ldsbase + (unsigned)((bufoff) + _i * 8192) + ldsw); } while (0)
; #define PG8_STAGEX(pb, gbase) glds16_s(voffX, (const void*)(gbase), ldsbase + (unsigned)(XOFF + (pb) * 4096) + ldsx)
; #define PG8_LDA(dst, b, h) do { _Pragma("unroll") for (int m = 0; m < 4; ++m) _Pragma("unroll") for (int k = 0; k < 2; ++k) dst[m][k] = *(const PG8_LAS bf16x8*)(lds + PG8_SA(b, h) + aoff + m * 2048 + k * 1024); } while (0)
; #define PG8_LDB(dst, b, h) do { _Pragma("unroll") for (int n = 0; n < 2; ++n) _Pragma("unroll") for (int k = 0; k < 2; ++k) dst[n][k] = *(const PG8_LAS bf16x8*)(lds + PG8_SB(b, h) + boff + n * 2048 + k * 1024); } while (0)
; #define PG8_LDX(pb, tp) do { _Pragma("unroll") for (int k = 0; k < 2; ++k) Ax[k] = *(const PG8_LAS bf16x8*)(lds + xoff + (pb) * 4096 + (tp) * 128 + k * 64); } while (0)
; #define PG8_MMA(ai, bj, At, Bt) do { __builtin_amdgcn_s_setprio(1); _Pragma("unroll") for (int m = 0; m < 4; ++m) _Pragma("unroll") for (int n = 0; n < 2; ++n) _Pragma("unroll") for (int k = 0; k < 2; ++k) \
;         acc[ai][bj][m][n] = __builtin_amdgcn_mfma_f32_16x16x32_bf16(Bt[n][k], At[m][k], acc[ai][bj][m][n], 0, 0, 0); __builtin_amdgcn_s_setprio(0); } while (0)
; #define PG8_WAIT_V(n) asm volatile("s_waitcnt vmcnt(" #n ")" ::: "memory")
; template <class Epi, class Sched, bool HM = false>
; __device__ __forceinline__ void gemm_phase(PG8_LAS unsigned char* lds, const Gemm g, const Sched& S, const Epi& E) {
;     ...
;             const bool last = (t == nt - 2);
;             const char* a1 = cA + (size_t)(t + 1) * kstep;
;             const char* a2 = last ? nA : cA + (size_t)(t + 2) * kstep; const char* b2 = last ? nB : cB + (size_t)(t + 2) * kstep;
;             const char* a3 = a2 + kstep; const char* b3 = b2 + kstep;
;             asm volatile("; uniform bases" : "+s"(a1), "+s"(a2), "+s"(a3), "+s"(b2), "+s"(b3));
;             if (last && has_next) S.a_ready(nxt);
;             const int pb = (t >> 1) & 1;
;             PG8_LDB(B0, 0, 0); PG8_LDB(B1, 0, 1); PG8_SCHED; PG8_LDA(At, 0, 0); if (hasx) PG8_LDX(pb, 0); PG8_STAGE(PG8_SA(1, 1), a1 + hstepA, voffA); PG8_STAGEX(pb ^ 1, a2 + xstep);
;             PG8_WAIT_V(9); PG8_WAIT_L(0); PG8_BAR; PG8_MMA(0, 0, At, B0); PG8_MMA(0, 1, At, B1); if (hasx) PG8_MMAX(); PG8_BAR; PG8_SCHED;
.LBB0_581:
	s_add_u32 s42, s82, 0xffffff80
	s_addc_u32 s43, s27, -1
	s_cmp_eq_u32 s23, 28
	s_cselect_b32 s8, s0, s82
	s_cselect_b32 s9, s1, s27
	s_cselect_b32 s35, s47, s44
	s_cselect_b32 s34, s46, s61
	s_add_u32 s4, s8, 0x80
	s_addc_u32 s5, s9, 0
	s_add_u32 s6, s34, 0x80
	s_addc_u32 s7, s35, 0
	v_add_u32_e32 v2, 0x10000, v234
	ds_read_b128 v[166:169], v2
	ds_read_b128 v[170:173], v2 offset:1024
	ds_read_b128 v[174:177], v2 offset:2048
	ds_read_b128 v[178:181], v2 offset:3072
	v_add_u32_e32 v2, 0x14000, v234
	ds_read_b128 v[150:153], v2
	ds_read_b128 v[154:157], v2 offset:1024
	ds_read_b128 v[158:161], v2 offset:2048
	s_waitcnt lgkmcnt(7)
	ds_read_b128 v[162:165], v2 offset:3072
	ds_read_b128 v[206:209], v235
	ds_read_b128 v[210:213], v235 offset:1024
	ds_read_b128 v[198:201], v235 offset:2048
	ds_read_b128 v[202:205], v235 offset:3072
	ds_read_b128 v[190:193], v235 offset:4096
	ds_read_b128 v[194:197], v235 offset:5120
	ds_read_b128 v[182:185], v235 offset:6144
	ds_read_b128 v[186:189], v235 offset:7168
	s_and_b32 s20, s22, 0x1000
	s_andn2_b64 s[40:41], exec, s[62:63]
	s_andn2_b64 vcc, exec, s[62:63]
	v_add_u32_e32 v2, s20, v231
	s_cbranch_vccnz .LBB0_583
	ds_read_b128 v[6:9], v2
	v_xor_b32_e32 v10, 64, v2
	ds_read_b128 v[10:13], v10
.LBB0_583:
	s_add_u32 s42, s42, 0x80000
	s_addc_u32 s43, s43, 0
	s_mov_b32 s21, m0
	s_mov_b32 m0, s13
	s_nop 0
	global_load_lds_dwordx4 v225, s[42:43]
	s_mov_b32 m0, s21
	s_nop 0
	s_mov_b32 s21, m0
	s_mov_b32 m0, s52
	s_nop 0
	global_load_lds_dwordx4 v227, s[42:43]
	s_mov_b32 m0, s21
	s_add_u32 s42, s8, 0x100000
	s_addc_u32 s43, s9, 0
	s_xor_b32 s20, s20, 0x21400
	s_add_i32 s20, s18, s20
	s_mov_b32 s21, m0
	s_mov_b32 m0, s20
	s_nop 0
	global_load_lds_dwordx4 v229, s[42:43]
	s_mov_b32 m0, s21
	s_waitcnt vmcnt(9)
	s_waitcnt lgkmcnt(0)
	s_barrier
	s_setprio 1
	s_waitcnt lgkmcnt(7)
	v_mfma_f32_16x16x32_bf16 v[146:149], v[166:169], v[206:209], v[146:149]
	v_mfma_f32_16x16x32_bf16 v[142:145], v[174:177], v[206:209], v[142:145]
	s_waitcnt lgkmcnt(5)
	v_mfma_f32_16x16x32_bf16 v[130:133], v[166:169], v[198:201], v[130:133]
	v_mfma_f32_16x16x32_bf16 v[126:129], v[174:177], v[198:201], v[126:129]
	s_waitcnt lgkmcnt(3)
	v_mfma_f32_16x16x32_bf16 v[114:117], v[166:169], v[190:193], v[114:117]
	v_mfma_f32_16x16x32_bf16 v[110:113], v[174:177], v[190:193], v[110:113]
	s_waitcnt lgkmcnt(1)
	v_mfma_f32_16x16x32_bf16 v[98:101], v[166:169], v[182:185], v[98:101]
	v_mfma_f32_16x16x32_bf16 v[94:97], v[174:177], v[182:185], v[94:97]
	v_mfma_f32_16x16x32_bf16 v[146:149], v[170:173], v[210:213], v[146:149]
	v_mfma_f32_16x16x32_bf16 v[142:145], v[178:181], v[210:213], v[142:145]
	v_mfma_f32_16x16x32_bf16 v[130:133], v[170:173], v[202:205], v[130:133]
	v_mfma_f32_16x16x32_bf16 v[126:129], v[178:181], v[202:205], v[126:129]
	v_mfma_f32_16x16x32_bf16 v[114:117], v[170:173], v[194:197], v[114:117]
	v_mfma_f32_16x16x32_bf16 v[110:113], v[178:181], v[194:197], v[110:113]
	s_waitcnt lgkmcnt(0)
	v_mfma_f32_16x16x32_bf16 v[98:101], v[170:173], v[186:189], v[98:101]
	v_mfma_f32_16x16x32_bf16 v[94:97], v[178:181], v[186:189], v[94:97]
	s_setprio 0
	s_setprio 1
	v_mfma_f32_16x16x32_bf16 v[138:141], v[150:153], v[206:209], v[138:141]
	v_mfma_f32_16x16x32_bf16 v[134:137], v[158:161], v[206:209], v[134:137]
	v_mfma_f32_16x16x32_bf16 v[122:125], v[150:153], v[198:201], v[122:125]
	v_mfma_f32_16x16x32_bf16 v[118:121], v[158:161], v[198:201], v[118:121]
	v_mfma_f32_16x16x32_bf16 v[106:109], v[150:153], v[190:193], v[106:109]
	v_mfma_f32_16x16x32_bf16 v[102:105], v[158:161], v[190:193], v[102:105]
	v_mfma_f32_16x16x32_bf16 v[90:93], v[150:153], v[182:185], v[90:93]
	v_mfma_f32_16x16x32_bf16 v[86:89], v[158:161], v[182:185], v[86:89]
	v_mfma_f32_16x16x32_bf16 v[138:141], v[154:157], v[210:213], v[138:141]
	v_mfma_f32_16x16x32_bf16 v[134:137], v[162:165], v[210:213], v[134:137]
	v_mfma_f32_16x16x32_bf16 v[122:125], v[154:157], v[202:205], v[122:125]
	v_mfma_f32_16x16x32_bf16 v[118:121], v[162:165], v[202:205], v[118:121]
	v_mfma_f32_16x16x32_bf16 v[106:109], v[154:157], v[194:197], v[106:109]
	v_mfma_f32_16x16x32_bf16 v[102:105], v[162:165], v[194:197], v[102:105]
	v_mfma_f32_16x16x32_bf16 v[90:93], v[154:157], v[186:189], v[90:93]
	v_mfma_f32_16x16x32_bf16 v[86:89], v[162:165], v[186:189], v[86:89]
	s_setprio 0
	s_andn2_b64 s[42:43], exec, s[96:97]
	s_and_b64 vcc, exec, s[40:41]
	s_cbranch_vccnz .LBB0_589
	s_and_b64 vcc, exec, s[42:43]
	s_cbranch_vccnz .LBB0_586
	v_mfma_f32_16x16x32_bf16 v[18:21], v[174:177], v[6:9], v[18:21]
	v_mfma_f32_16x16x32_bf16 v[14:17], v[158:161], v[6:9], v[14:17]
	v_mfma_f32_16x16x32_bf16 v[18:21], v[178:181], v[10:13], v[18:21]
	v_mfma_f32_16x16x32_bf16 v[14:17], v[162:165], v[10:13], v[14:17]
	s_branch .LBB0_589

; #define PG8_STAGE(bufoff, gbase, voff) do { _Pragma("unroll") for (int _i = 0; _i < 2; ++_i) glds16_s((voff)[_i], (const void*)(gbase), ldsbase + (unsigned)((bufoff) + _i * 8192) + ldsw); } while (0)
; #define PG8_LDA(dst, b, h) do { _Pragma("unroll") for (int m = 0; m < 4; ++m) _Pragma("unroll") for (int k = 0; k < 2; ++k) dst[m][k] = *(const PG8_LAS bf16x8*)(lds + PG8_SA(b, h) + aoff + m * 2048 + k * 1024); } while (0)
; #define PG8_LDB(dst, b, h) do { _Pragma("unroll") for (int n = 0; n < 2; ++n) _Pragma("unroll") for (int k = 0; k < 2; ++k) dst[n][k] = *(const PG8_LAS bf16x8*)(lds + PG8_SB(b, h) + boff + n * 2048 + k * 1024); } while (0)
; #define PG8_LDX(pb, tp) do { _Pragma("unroll") for (int k = 0; k < 2; ++k) Ax[k] = *(const PG8_LAS bf16x8*)(lds + xoff + (pb) * 4096 + (tp) * 128 + k * 64); } while (0)
; #define PG8_MMA(ai, bj, At, Bt) do { __builtin_amdgcn_s_setprio(1); _Pragma("unroll") for (int m = 0; m < 4; ++m) _Pragma("unroll") for (int n = 0; n < 2; ++n) _Pragma("unroll") for (int k = 0; k < 2; ++k) \
;         acc[ai][bj][m][n] = __builtin_amdgcn_mfma_f32_16x16x32_bf16(Bt[n][k], At[m][k], acc[ai][bj][m][n], 0, 0, 0); __builtin_amdgcn_s_setprio(0); } while (0)
; #define PG8_WAIT_V(n) asm volatile("s_waitcnt vmcnt(" #n ")" ::: "memory")
; #define PG8_WAIT_L(n) asm volatile("s_waitcnt lgkmcnt(" #n ")" ::: "memory")
; #define PG8_BAR __builtin_amdgcn_s_barrier()
; #define PG8_SCHED __builtin_amdgcn_sched_barrier(0)
; template <class Epi, class Sched, bool HM = false>
; __device__ __forceinline__ void gemm_phase(PG8_LAS unsigned char* lds, const Gemm g, const Sched& S, const Epi& E) {
;     ...
;             PG8_LDB(B0, 1, 0); PG8_LDB(B1, 1, 1); PG8_SCHED; PG8_LDA(At, 1, 0); if (hasx) PG8_LDX(pb, 1); PG8_STAGE(PG8_SA(0, 1), a2 + hstepA, voffA);
;             PG8_WAIT_V(9); PG8_WAIT_L(0); PG8_BAR; PG8_MMA(0, 0, At, B0); PG8_MMA(0, 1, At, B1); if (hasx) PG8_MMAX(); PG8_BAR; PG8_SCHED;
.LBB0_591:
	s_add_u32 s8, s8, 0x80000
	s_addc_u32 s9, s9, 0
	s_mov_b32 s20, m0
	s_mov_b32 m0, s19
	s_nop 0
	global_load_lds_dwordx4 v225, s[8:9]
	s_mov_b32 m0, s20
	s_nop 0
	s_mov_b32 s20, m0
	s_mov_b32 m0, s28
	s_nop 0
	global_load_lds_dwordx4 v227, s[8:9]
	s_mov_b32 m0, s20
	s_waitcnt vmcnt(9)
	s_waitcnt lgkmcnt(0)
	s_barrier
	s_setprio 1
	s_waitcnt lgkmcnt(7)
	v_mfma_f32_16x16x32_bf16 v[146:149], v[166:169], v[206:209], v[146:149]
	v_mfma_f32_16x16x32_bf16 v[142:145], v[174:177], v[206:209], v[142:145]
	s_waitcnt lgkmcnt(5)
	v_mfma_f32_16x16x32_bf16 v[130:133], v[166:169], v[198:201], v[130:133]
	v_mfma_f32_16x16x32_bf16 v[126:129], v[174:177], v[198:201], v[126:129]
	s_waitcnt lgkmcnt(3)
	v_mfma_f32_16x16x32_bf16 v[114:117], v[166:169], v[190:193], v[114:117]
	v_mfma_f32_16x16x32_bf16 v[110:113], v[174:177], v[190:193], v[110:113]
	s_waitcnt lgkmcnt(1)
	v_mfma_f32_16x16x32_bf16 v[98:101], v[166:169], v[182:185], v[98:101]
	v_mfma_f32_16x16x32_bf16 v[94:97], v[174:177], v[182:185], v[94:97]
	v_mfma_f32_16x16x32_bf16 v[146:149], v[170:173], v[210:213], v[146:149]
	v_mfma_f32_16x16x32_bf16 v[142:145], v[178:181], v[210:213], v[142:145]
	v_mfma_f32_16x16x32_bf16 v[130:133], v[170:173], v[202:205], v[130:133]
	v_mfma_f32_16x16x32_bf16 v[126:129], v[178:181], v[202:205], v[126:129]
	v_mfma_f32_16x16x32_bf16 v[114:117], v[170:173], v[194:197], v[114:117]
	v_mfma_f32_16x16x32_bf16 v[110:113], v[178:181], v[194:197], v[110:113]
	s_waitcnt lgkmcnt(0)
	v_mfma_f32_16x16x32_bf16 v[98:101], v[170:173], v[186:189], v[98:101]
	v_mfma_f32_16x16x32_bf16 v[94:97], v[178:181], v[186:189], v[94:97]
	s_setprio 0
	s_setprio 1
	v_mfma_f32_16x16x32_bf16 v[138:141], v[150:153], v[206:209], v[138:141]
	v_mfma_f32_16x16x32_bf16 v[134:137], v[158:161], v[206:209], v[134:137]
	v_mfma_f32_16x16x32_bf16 v[122:125], v[150:153], v[198:201], v[122:125]
	v_mfma_f32_16x16x32_bf16 v[118:121], v[158:161], v[198:201], v[118:121]
	v_mfma_f32_16x16x32_bf16 v[106:109], v[150:153], v[190:193], v[106:109]
	v_mfma_f32_16x16x32_bf16 v[102:105], v[158:161], v[190:193], v[102:105]
	v_mfma_f32_16x16x32_bf16 v[90:93], v[150:153], v[182:185], v[90:93]
	v_mfma_f32_16x16x32_bf16 v[86:89], v[158:161], v[182:185], v[86:89]
	v_mfma_f32_16x16x32_bf16 v[138:141], v[154:157], v[210:213], v[138:141]
	v_mfma_f32_16x16x32_bf16 v[134:137], v[162:165], v[210:213], v[134:137]
	v_mfma_f32_16x16x32_bf16 v[122:125], v[154:157], v[202:205], v[122:125]
	v_mfma_f32_16x16x32_bf16 v[118:121], v[162:165], v[202:205], v[118:121]
	v_mfma_f32_16x16x32_bf16 v[106:109], v[154:157], v[194:197], v[106:109]
	v_mfma_f32_16x16x32_bf16 v[102:105], v[162:165], v[194:197], v[102:105]
	v_mfma_f32_16x16x32_bf16 v[90:93], v[154:157], v[186:189], v[90:93]
	v_mfma_f32_16x16x32_bf16 v[86:89], v[162:165], v[186:189], v[86:89]
	s_setprio 0
	s_and_b64 vcc, exec, s[40:41]
	s_cbranch_vccnz .LBB0_580
	s_and_b64 vcc, exec, s[42:43]
	s_cbranch_vccnz .LBB0_594
	v_mfma_f32_16x16x32_bf16 v[18:21], v[174:177], v[6:9], v[18:21]
	v_mfma_f32_16x16x32_bf16 v[14:17], v[158:161], v[6:9], v[14:17]
	v_mfma_f32_16x16x32_bf16 v[18:21], v[178:181], v[10:13], v[18:21]
	v_mfma_f32_16x16x32_bf16 v[14:17], v[162:165], v[10:13], v[14:17]
	s_branch .LBB0_579

; #define PG8_STAGE(bufoff, gbase, voff) do { _Pragma("unroll") for (int _i = 0; _i < 2; ++_i) glds16_s((voff)[_i], (const void*)(gbase), ldsbase + (unsigned)((bufoff) + _i * 8192) + ldsw); } while (0)
; #define PG8_STAGEX(pb, gbase) glds16_s(voffX, (const void*)(gbase), ldsbase + (unsigned)(XOFF + (pb) * 4096) + ldsx)
; #define PG8_LDA(dst, b, h) do { _Pragma("unroll") for (int m = 0; m < 4; ++m) _Pragma("unroll") for (int k = 0; k < 2; ++k) dst[m][k] = *(const PG8_LAS bf16x8*)(lds + PG8_SA(b, h) + aoff + m * 2048 + k * 1024); } while (0)
; #define PG8_LDB(dst, b, h) do { _Pragma("unroll") for (int n = 0; n < 2; ++n) _Pragma("unroll") for (int k = 0; k < 2; ++k) dst[n][k] = *(const PG8_LAS bf16x8*)(lds + PG8_SB(b, h) + boff + n * 2048 + k * 1024); } while (0)
; #define PG8_LDX(pb, tp) do { _Pragma("unroll") for (int k = 0; k < 2; ++k) Ax[k] = *(const PG8_LAS bf16x8*)(lds + xoff + (pb) * 4096 + (tp) * 128 + k * 64); } while (0)
; #define PG8_MMA(ai, bj, At, Bt) do { __builtin_amdgcn_s_setprio(1); _Pragma("unroll") for (int m = 0; m < 4; ++m) _Pragma("unroll") for (int n = 0; n < 2; ++n) _Pragma("unroll") for (int k = 0; k < 2; ++k) \
;         acc[ai][bj][m][n] = __builtin_amdgcn_mfma_f32_16x16x32_bf16(Bt[n][k], At[m][k], acc[ai][bj][m][n], 0, 0, 0); __builtin_amdgcn_s_setprio(0); } while (0)
; #define PG8_WAIT_V(n) asm volatile("s_waitcnt vmcnt(" #n ")" ::: "memory")
; template <class Epi, class Sched, bool HM = false>
; __device__ __forceinline__ void gemm_phase(PG8_LAS unsigned char* lds, const Gemm g, const Sched& S, const Epi& E) {
;     ...
;             const bool last = (t == nt - 2);
;             const char* a1 = cA + (size_t)(t + 1) * kstep;
;             const char* a2 = last ? nA : cA + (size_t)(t + 2) * kstep; const char* b2 = last ? nB : cB + (size_t)(t + 2) * kstep;
;             const char* a3 = a2 + kstep; const char* b3 = b2 + kstep;
;             asm volatile("; uniform bases" : "+s"(a1), "+s"(a2), "+s"(a3), "+s"(b2), "+s"(b3));
;             if (last && has_next) S.a_ready(nxt);
;             const int pb = (t >> 1) & 1;
;             PG8_LDB(B0, 0, 0); PG8_LDB(B1, 0, 1); PG8_SCHED; PG8_LDA(At, 0, 0); if (hasx) PG8_LDX(pb, 0); PG8_STAGE(PG8_SA(1, 1), a1 + hstepA, voffA); PG8_STAGEX(pb ^ 1, a2 + xstep);
;             PG8_WAIT_V(9); PG8_WAIT_L(0); PG8_BAR; PG8_MMA(0, 0, At, B0); PG8_MMA(0, 1, At, B1); if (hasx) PG8_MMAX(); PG8_BAR; PG8_SCHED;
.LBB0_987:
	s_add_u32 s42, s27, 0xffffff80
	s_addc_u32 s43, s82, -1
	s_cmp_eq_u32 s23, 28
	s_cselect_b32 s8, s76, s27
	s_cselect_b32 s9, s77, s82
	s_cselect_b32 s35, s79, s90
	s_cselect_b32 s34, s78, s89
	s_add_u32 s4, s8, 0x80
	s_addc_u32 s5, s9, 0
	s_add_u32 s6, s34, 0x80
	s_addc_u32 s7, s35, 0
	v_add_u32_e32 v2, 0x10000, v234
	ds_read_b128 v[166:169], v2
	ds_read_b128 v[170:173], v2 offset:1024
	ds_read_b128 v[174:177], v2 offset:2048
	ds_read_b128 v[178:181], v2 offset:3072
	v_add_u32_e32 v2, 0x14000, v234
	ds_read_b128 v[150:153], v2
	ds_read_b128 v[154:157], v2 offset:1024
	ds_read_b128 v[158:161], v2 offset:2048
	s_waitcnt lgkmcnt(7)
	ds_read_b128 v[162:165], v2 offset:3072
	ds_read_b128 v[206:209], v235
	ds_read_b128 v[210:213], v235 offset:1024
	ds_read_b128 v[198:201], v235 offset:2048
	ds_read_b128 v[202:205], v235 offset:3072
	ds_read_b128 v[190:193], v235 offset:4096
	ds_read_b128 v[194:197], v235 offset:5120
	ds_read_b128 v[182:185], v235 offset:6144
	ds_read_b128 v[186:189], v235 offset:7168
	s_and_b32 s20, s22, 0x1000
	s_andn2_b64 s[40:41], exec, s[54:55]
	s_andn2_b64 vcc, exec, s[54:55]
	v_add_u32_e32 v2, s20, v232
	s_cbranch_vccnz .LBB0_989
	ds_read_b128 v[6:9], v2
	v_xor_b32_e32 v10, 64, v2
	ds_read_b128 v[10:13], v10
.LBB0_989:
	s_add_u32 s42, s42, 0x80000
	s_addc_u32 s43, s43, 0
	s_mov_b32 s21, m0
	s_mov_b32 m0, s59
	s_nop 0
	global_load_lds_dwordx4 v225, s[42:43]
	s_mov_b32 m0, s21
	s_nop 0
	s_mov_b32 s21, m0
	s_mov_b32 m0, s83
	s_nop 0
	global_load_lds_dwordx4 v227, s[42:43]
	s_mov_b32 m0, s21
	s_add_u32 s42, s8, 0x100000
	s_addc_u32 s43, s9, 0
	s_xor_b32 s20, s20, 0x21400
	s_add_i32 s20, s30, s20
	s_mov_b32 s21, m0
	s_mov_b32 m0, s20
	s_nop 0
	global_load_lds_dwordx4 v229, s[42:43]
	s_mov_b32 m0, s21
	s_waitcnt vmcnt(9)
	s_waitcnt lgkmcnt(0)
	s_barrier
	s_setprio 1
	s_waitcnt lgkmcnt(7)
	v_mfma_f32_16x16x32_bf16 v[146:149], v[166:169], v[206:209], v[146:149]
	v_mfma_f32_16x16x32_bf16 v[142:145], v[174:177], v[206:209], v[142:145]
	s_waitcnt lgkmcnt(5)
	v_mfma_f32_16x16x32_bf16 v[138:141], v[166:169], v[198:201], v[138:141]
	v_mfma_f32_16x16x32_bf16 v[130:133], v[174:177], v[198:201], v[130:133]
	s_waitcnt lgkmcnt(3)
	v_mfma_f32_16x16x32_bf16 v[122:125], v[166:169], v[190:193], v[122:125]
	v_mfma_f32_16x16x32_bf16 v[114:117], v[174:177], v[190:193], v[114:117]
	s_waitcnt lgkmcnt(1)
	v_mfma_f32_16x16x32_bf16 v[106:109], v[166:169], v[182:185], v[106:109]
	v_mfma_f32_16x16x32_bf16 v[98:101], v[174:177], v[182:185], v[98:101]
	v_mfma_f32_16x16x32_bf16 v[146:149], v[170:173], v[210:213], v[146:149]
	v_mfma_f32_16x16x32_bf16 v[142:145], v[178:181], v[210:213], v[142:145]
	v_mfma_f32_16x16x32_bf16 v[138:141], v[170:173], v[202:205], v[138:141]
	v_mfma_f32_16x16x32_bf16 v[130:133], v[178:181], v[202:205], v[130:133]
	v_mfma_f32_16x16x32_bf16 v[122:125], v[170:173], v[194:197], v[122:125]
	v_mfma_f32_16x16x32_bf16 v[114:117], v[178:181], v[194:197], v[114:117]
	s_waitcnt lgkmcnt(0)
	v_mfma_f32_16x16x32_bf16 v[106:109], v[170:173], v[186:189], v[106:109]
	v_mfma_f32_16x16x32_bf16 v[98:101], v[178:181], v[186:189], v[98:101]
	s_setprio 0
	s_setprio 1
	v_mfma_f32_16x16x32_bf16 v[134:137], v[150:153], v[206:209], v[134:137]
	v_mfma_f32_16x16x32_bf16 v[126:129], v[158:161], v[206:209], v[126:129]
	v_mfma_f32_16x16x32_bf16 v[118:121], v[150:153], v[198:201], v[118:121]
	v_mfma_f32_16x16x32_bf16 v[110:113], v[158:161], v[198:201], v[110:113]
	v_mfma_f32_16x16x32_bf16 v[102:105], v[150:153], v[190:193], v[102:105]
	v_mfma_f32_16x16x32_bf16 v[94:97], v[158:161], v[190:193], v[94:97]
	v_mfma_f32_16x16x32_bf16 v[90:93], v[150:153], v[182:185], v[90:93]
	v_mfma_f32_16x16x32_bf16 v[86:89], v[158:161], v[182:185], v[86:89]
	v_mfma_f32_16x16x32_bf16 v[134:137], v[154:157], v[210:213], v[134:137]
	v_mfma_f32_16x16x32_bf16 v[126:129], v[162:165], v[210:213], v[126:129]
	v_mfma_f32_16x16x32_bf16 v[118:121], v[154:157], v[202:205], v[118:121]
	v_mfma_f32_16x16x32_bf16 v[110:113], v[162:165], v[202:205], v[110:113]
	v_mfma_f32_16x16x32_bf16 v[102:105], v[154:157], v[194:197], v[102:105]
	v_mfma_f32_16x16x32_bf16 v[94:97], v[162:165], v[194:197], v[94:97]
	v_mfma_f32_16x16x32_bf16 v[90:93], v[154:157], v[186:189], v[90:93]
	v_mfma_f32_16x16x32_bf16 v[86:89], v[162:165], v[186:189], v[86:89]
	s_setprio 0
	s_andn2_b64 s[42:43], exec, s[62:63]
	s_and_b64 vcc, exec, s[40:41]
	s_cbranch_vccnz .LBB0_995
	s_and_b64 vcc, exec, s[42:43]
	s_cbranch_vccnz .LBB0_992
	v_mfma_f32_16x16x32_bf16 v[18:21], v[174:177], v[6:9], v[18:21]
	v_mfma_f32_16x16x32_bf16 v[14:17], v[158:161], v[6:9], v[14:17]
	v_mfma_f32_16x16x32_bf16 v[18:21], v[178:181], v[10:13], v[18:21]
	v_mfma_f32_16x16x32_bf16 v[14:17], v[162:165], v[10:13], v[14:17]
	s_branch .LBB0_995

; #define PG8_STAGE(bufoff, gbase, voff) do { _Pragma("unroll") for (int _i = 0; _i < 2; ++_i) glds16_s((voff)[_i], (const void*)(gbase), ldsbase + (unsigned)((bufoff) + _i * 8192) + ldsw); } while (0)
; #define PG8_LDA(dst, b, h) do { _Pragma("unroll") for (int m = 0; m < 4; ++m) _Pragma("unroll") for (int k = 0; k < 2; ++k) dst[m][k] = *(const PG8_LAS bf16x8*)(lds + PG8_SA(b, h) + aoff + m * 2048 + k * 1024); } while (0)
; #define PG8_LDB(dst, b, h) do { _Pragma("unroll") for (int n = 0; n < 2; ++n) _Pragma("unroll") for (int k = 0; k < 2; ++k) dst[n][k] = *(const PG8_LAS bf16x8*)(lds + PG8_SB(b, h) + boff + n * 2048 + k * 1024); } while (0)
; #define PG8_LDX(pb, tp) do { _Pragma("unroll") for (int k = 0; k < 2; ++k) Ax[k] = *(const PG8_LAS bf16x8*)(lds + xoff + (pb) * 4096 + (tp) * 128 + k * 64); } while (0)
; #define PG8_MMA(ai, bj, At, Bt) do { __builtin_amdgcn_s_setprio(1); _Pragma("unroll") for (int m = 0; m < 4; ++m) _Pragma("unroll") for (int n = 0; n < 2; ++n) _Pragma("unroll") for (int k = 0; k < 2; ++k) \
;         acc[ai][bj][m][n] = __builtin_amdgcn_mfma_f32_16x16x32_bf16(Bt[n][k], At[m][k], acc[ai][bj][m][n], 0, 0, 0); __builtin_amdgcn_s_setprio(0); } while (0)
; #define PG8_WAIT_V(n) asm volatile("s_waitcnt vmcnt(" #n ")" ::: "memory")
; #define PG8_WAIT_L(n) asm volatile("s_waitcnt lgkmcnt(" #n ")" ::: "memory")
; #define PG8_BAR __builtin_amdgcn_s_barrier()
; #define PG8_SCHED __builtin_amdgcn_sched_barrier(0)
; template <class Epi, class Sched, bool HM = false>
; __device__ __forceinline__ void gemm_phase(PG8_LAS unsigned char* lds, const Gemm g, const Sched& S, const Epi& E) {
;     ...
;             PG8_LDB(B0, 1, 0); PG8_LDB(B1, 1, 1); PG8_SCHED; PG8_LDA(At, 1, 0); if (hasx) PG8_LDX(pb, 1); PG8_STAGE(PG8_SA(0, 1), a2 + hstepA, voffA);
;             PG8_WAIT_V(9); PG8_WAIT_L(0); PG8_BAR; PG8_MMA(0, 0, At, B0); PG8_MMA(0, 1, At, B1); if (hasx) PG8_MMAX(); PG8_BAR; PG8_SCHED;
.LBB0_997:
	s_add_u32 s8, s8, 0x80000
	s_addc_u32 s9, s9, 0
	s_mov_b32 s20, m0
	s_mov_b32 m0, s31
	s_nop 0
	global_load_lds_dwordx4 v225, s[8:9]
	s_mov_b32 m0, s20
	s_nop 0
	s_mov_b32 s20, m0
	s_mov_b32 m0, s36
	s_nop 0
	global_load_lds_dwordx4 v227, s[8:9]
	s_mov_b32 m0, s20
	s_waitcnt vmcnt(9)
	s_waitcnt lgkmcnt(0)
	s_barrier
	s_setprio 1
	s_waitcnt lgkmcnt(7)
	v_mfma_f32_16x16x32_bf16 v[146:149], v[166:169], v[206:209], v[146:149]
	v_mfma_f32_16x16x32_bf16 v[142:145], v[174:177], v[206:209], v[142:145]
	s_waitcnt lgkmcnt(5)
	v_mfma_f32_16x16x32_bf16 v[138:141], v[166:169], v[198:201], v[138:141]
	v_mfma_f32_16x16x32_bf16 v[130:133], v[174:177], v[198:201], v[130:133]
	s_waitcnt lgkmcnt(3)
	v_mfma_f32_16x16x32_bf16 v[122:125], v[166:169], v[190:193], v[122:125]
	v_mfma_f32_16x16x32_bf16 v[114:117], v[174:177], v[190:193], v[114:117]
	s_waitcnt lgkmcnt(1)
	v_mfma_f32_16x16x32_bf16 v[106:109], v[166:169], v[182:185], v[106:109]
	v_mfma_f32_16x16x32_bf16 v[98:101], v[174:177], v[182:185], v[98:101]
	v_mfma_f32_16x16x32_bf16 v[146:149], v[170:173], v[210:213], v[146:149]
	v_mfma_f32_16x16x32_bf16 v[142:145], v[178:181], v[210:213], v[142:145]
	v_mfma_f32_16x16x32_bf16 v[138:141], v[170:173], v[202:205], v[138:141]
	v_mfma_f32_16x16x32_bf16 v[130:133], v[178:181], v[202:205], v[130:133]
	v_mfma_f32_16x16x32_bf16 v[122:125], v[170:173], v[194:197], v[122:125]
	v_mfma_f32_16x16x32_bf16 v[114:117], v[178:181], v[194:197], v[114:117]
	s_waitcnt lgkmcnt(0)
	v_mfma_f32_16x16x32_bf16 v[106:109], v[170:173], v[186:189], v[106:109]
	v_mfma_f32_16x16x32_bf16 v[98:101], v[178:181], v[186:189], v[98:101]
	s_setprio 0
	s_setprio 1
	v_mfma_f32_16x16x32_bf16 v[134:137], v[150:153], v[206:209], v[134:137]
	v_mfma_f32_16x16x32_bf16 v[126:129], v[158:161], v[206:209], v[126:129]
	v_mfma_f32_16x16x32_bf16 v[118:121], v[150:153], v[198:201], v[118:121]
	v_mfma_f32_16x16x32_bf16 v[110:113], v[158:161], v[198:201], v[110:113]
	v_mfma_f32_16x16x32_bf16 v[102:105], v[150:153], v[190:193], v[102:105]
	v_mfma_f32_16x16x32_bf16 v[94:97], v[158:161], v[190:193], v[94:97]
	v_mfma_f32_16x16x32_bf16 v[90:93], v[150:153], v[182:185], v[90:93]
	v_mfma_f32_16x16x32_bf16 v[86:89], v[158:161], v[182:185], v[86:89]
	v_mfma_f32_16x16x32_bf16 v[134:137], v[154:157], v[210:213], v[134:137]
	v_mfma_f32_16x16x32_bf16 v[126:129], v[162:165], v[210:213], v[126:129]
	v_mfma_f32_16x16x32_bf16 v[118:121], v[154:157], v[202:205], v[118:121]
	v_mfma_f32_16x16x32_bf16 v[110:113], v[162:165], v[202:205], v[110:113]
	v_mfma_f32_16x16x32_bf16 v[102:105], v[154:157], v[194:197], v[102:105]
	v_mfma_f32_16x16x32_bf16 v[94:97], v[162:165], v[194:197], v[94:97]
	v_mfma_f32_16x16x32_bf16 v[90:93], v[154:157], v[186:189], v[90:93]
	v_mfma_f32_16x16x32_bf16 v[86:89], v[162:165], v[186:189], v[86:89]
	s_setprio 0
	s_and_b64 vcc, exec, s[40:41]
	s_cbranch_vccnz .LBB0_986
	s_and_b64 vcc, exec, s[42:43]
	s_cbranch_vccnz .LBB0_1000
	v_mfma_f32_16x16x32_bf16 v[18:21], v[174:177], v[6:9], v[18:21]
	v_mfma_f32_16x16x32_bf16 v[14:17], v[158:161], v[6:9], v[14:17]
	v_mfma_f32_16x16x32_bf16 v[18:21], v[178:181], v[10:13], v[18:21]
	v_mfma_f32_16x16x32_bf16 v[14:17], v[162:165], v[10:13], v[14:17]
	s_branch .LBB0_985

; #define PG8_STAGE(bufoff, gbase, voff) do { _Pragma("unroll") for (int _i = 0; _i < 2; ++_i) glds16_s((voff)[_i], (const void*)(gbase), ldsbase + (unsigned)((bufoff) + _i * 8192) + ldsw); } while (0)
; #define PG8_STAGEX(pb, gbase) glds16_s(voffX, (const void*)(gbase), ldsbase + (unsigned)(XOFF + (pb) * 4096) + ldsx)
; #define PG8_LDA(dst, b, h) do { _Pragma("unroll") for (int m = 0; m < 4; ++m) _Pragma("unroll") for (int k = 0; k < 2; ++k) dst[m][k] = *(const PG8_LAS bf16x8*)(lds + PG8_SA(b, h) + aoff + m * 2048 + k * 1024); } while (0)
; #define PG8_LDB(dst, b, h) do { _Pragma("unroll") for (int n = 0; n < 2; ++n) _Pragma("unroll") for (int k = 0; k < 2; ++k) dst[n][k] = *(const PG8_LAS bf16x8*)(lds + PG8_SB(b, h) + boff + n * 2048 + k * 1024); } while (0)
; #define PG8_LDX(pb, tp) do { _Pragma("unroll") for (int k = 0; k < 2; ++k) Ax[k] = *(const PG8_LAS bf16x8*)(lds + xoff + (pb) * 4096 + (tp) * 128 + k * 64); } while (0)
; #define PG8_MMA(ai, bj, At, Bt) do { __builtin_amdgcn_s_setprio(1); _Pragma("unroll") for (int m = 0; m < 4; ++m) _Pragma("unroll") for (int n = 0; n < 2; ++n) _Pragma("unroll") for (int k = 0; k < 2; ++k) \
;         acc[ai][bj][m][n] = __builtin_amdgcn_mfma_f32_16x16x32_bf16(Bt[n][k], At[m][k], acc[ai][bj][m][n], 0, 0, 0); __builtin_amdgcn_s_setprio(0); } while (0)
; #define PG8_WAIT_V(n) asm volatile("s_waitcnt vmcnt(" #n ")" ::: "memory")
; template <class Epi, class Sched, bool HM = false>
; __device__ __forceinline__ void gemm_phase(PG8_LAS unsigned char* lds, const Gemm g, const Sched& S, const Epi& E) {
;     ...
;             const bool last = (t == nt - 2);
;             const char* a1 = cA + (size_t)(t + 1) * kstep;
;             const char* a2 = last ? nA : cA + (size_t)(t + 2) * kstep; const char* b2 = last ? nB : cB + (size_t)(t + 2) * kstep;
;             const char* a3 = a2 + kstep; const char* b3 = b2 + kstep;
;             asm volatile("; uniform bases" : "+s"(a1), "+s"(a2), "+s"(a3), "+s"(b2), "+s"(b3));
;             if (last && has_next) S.a_ready(nxt);
;             const int pb = (t >> 1) & 1;
;             PG8_LDB(B0, 0, 0); PG8_LDB(B1, 0, 1); PG8_SCHED; PG8_LDA(At, 0, 0); if (hasx) PG8_LDX(pb, 0); PG8_STAGE(PG8_SA(1, 1), a1 + hstepA, voffA); PG8_STAGEX(pb ^ 1, a2 + xstep);
;             PG8_WAIT_V(9); PG8_WAIT_L(0); PG8_BAR; PG8_MMA(0, 0, At, B0); PG8_MMA(0, 1, At, B1); if (hasx) PG8_MMAX(); PG8_BAR; PG8_SCHED;
.LBB0_1269:
	s_add_u32 s40, s27, 0xffffff80
	s_addc_u32 s41, s82, -1
	s_cmpk_eq_i32 s23, 0x54
	s_cselect_b32 s8, s58, s27
	s_cselect_b32 s9, s59, s82
	s_cselect_b32 s35, s61, s89
	s_cselect_b32 s34, s60, s88
	s_add_u32 s4, s8, 0x80
	s_addc_u32 s5, s9, 0
	s_add_u32 s6, s34, 0x80
	s_addc_u32 s7, s35, 0
	v_add_u32_e32 v2, 0x10000, v234
	ds_read_b128 v[166:169], v2
	ds_read_b128 v[170:173], v2 offset:1024
	ds_read_b128 v[174:177], v2 offset:2048
	ds_read_b128 v[178:181], v2 offset:3072
	v_add_u32_e32 v2, 0x14000, v234
	ds_read_b128 v[150:153], v2
	ds_read_b128 v[154:157], v2 offset:1024
	ds_read_b128 v[158:161], v2 offset:2048
	s_waitcnt lgkmcnt(7)
	ds_read_b128 v[162:165], v2 offset:3072
	ds_read_b128 v[206:209], v235
	ds_read_b128 v[210:213], v235 offset:1024
	ds_read_b128 v[198:201], v235 offset:2048
	ds_read_b128 v[202:205], v235 offset:3072
	ds_read_b128 v[190:193], v235 offset:4096
	ds_read_b128 v[194:197], v235 offset:5120
	ds_read_b128 v[182:185], v235 offset:6144
	ds_read_b128 v[186:189], v235 offset:7168
	s_and_b32 s20, s22, 0x1000
	s_andn2_b64 s[38:39], exec, s[54:55]
	s_andn2_b64 vcc, exec, s[54:55]
	v_add_u32_e32 v2, s20, v232
	s_cbranch_vccnz .LBB0_1271
	ds_read_b128 v[6:9], v2
	v_xor_b32_e32 v10, 64, v2
	ds_read_b128 v[10:13], v10
.LBB0_1271:
	s_add_u32 s40, s40, 0x160000
	s_addc_u32 s41, s41, 0
	s_mov_b32 s21, m0
	s_mov_b32 m0, s76
	s_nop 0
	global_load_lds_dwordx4 v225, s[40:41]
	s_mov_b32 m0, s21
	s_nop 0
	s_mov_b32 s21, m0
	s_mov_b32 m0, s77
	s_nop 0
	global_load_lds_dwordx4 v227, s[40:41]
	s_mov_b32 m0, s21
	s_add_u32 s40, s8, 0x2c0000
	s_addc_u32 s41, s9, 0
	s_xor_b32 s20, s20, 0x21400
	s_add_i32 s20, s29, s20
	s_mov_b32 s21, m0
	s_mov_b32 m0, s20
	s_nop 0
	global_load_lds_dwordx4 v229, s[40:41]
	s_mov_b32 m0, s21
	s_waitcnt vmcnt(9)
	s_waitcnt lgkmcnt(0)
	s_barrier
	s_setprio 1
	s_waitcnt lgkmcnt(7)
	v_mfma_f32_16x16x32_bf16 v[146:149], v[166:169], v[206:209], v[146:149]
	v_mfma_f32_16x16x32_bf16 v[142:145], v[174:177], v[206:209], v[142:145]
	s_waitcnt lgkmcnt(5)
	v_mfma_f32_16x16x32_bf16 v[138:141], v[166:169], v[198:201], v[138:141]
	v_mfma_f32_16x16x32_bf16 v[130:133], v[174:177], v[198:201], v[130:133]
	s_waitcnt lgkmcnt(3)
	v_mfma_f32_16x16x32_bf16 v[122:125], v[166:169], v[190:193], v[122:125]
	v_mfma_f32_16x16x32_bf16 v[114:117], v[174:177], v[190:193], v[114:117]
	s_waitcnt lgkmcnt(1)
	v_mfma_f32_16x16x32_bf16 v[106:109], v[166:169], v[182:185], v[106:109]
	v_mfma_f32_16x16x32_bf16 v[98:101], v[174:177], v[182:185], v[98:101]
	v_mfma_f32_16x16x32_bf16 v[146:149], v[170:173], v[210:213], v[146:149]
	v_mfma_f32_16x16x32_bf16 v[142:145], v[178:181], v[210:213], v[142:145]
	v_mfma_f32_16x16x32_bf16 v[138:141], v[170:173], v[202:205], v[138:141]
	v_mfma_f32_16x16x32_bf16 v[130:133], v[178:181], v[202:205], v[130:133]
	v_mfma_f32_16x16x32_bf16 v[122:125], v[170:173], v[194:197], v[122:125]
	v_mfma_f32_16x16x32_bf16 v[114:117], v[178:181], v[194:197], v[114:117]
	s_waitcnt lgkmcnt(0)
	v_mfma_f32_16x16x32_bf16 v[106:109], v[170:173], v[186:189], v[106:109]
	v_mfma_f32_16x16x32_bf16 v[98:101], v[178:181], v[186:189], v[98:101]
	s_setprio 0
	s_setprio 1
	v_mfma_f32_16x16x32_bf16 v[134:137], v[150:153], v[206:209], v[134:137]
	v_mfma_f32_16x16x32_bf16 v[126:129], v[158:161], v[206:209], v[126:129]
	v_mfma_f32_16x16x32_bf16 v[118:121], v[150:153], v[198:201], v[118:121]
	v_mfma_f32_16x16x32_bf16 v[110:113], v[158:161], v[198:201], v[110:113]
	v_mfma_f32_16x16x32_bf16 v[102:105], v[150:153], v[190:193], v[102:105]
	v_mfma_f32_16x16x32_bf16 v[94:97], v[158:161], v[190:193], v[94:97]
	v_mfma_f32_16x16x32_bf16 v[90:93], v[150:153], v[182:185], v[90:93]
	v_mfma_f32_16x16x32_bf16 v[86:89], v[158:161], v[182:185], v[86:89]
	v_mfma_f32_16x16x32_bf16 v[134:137], v[154:157], v[210:213], v[134:137]
	v_mfma_f32_16x16x32_bf16 v[126:129], v[162:165], v[210:213], v[126:129]
	v_mfma_f32_16x16x32_bf16 v[118:121], v[154:157], v[202:205], v[118:121]
	v_mfma_f32_16x16x32_bf16 v[110:113], v[162:165], v[202:205], v[110:113]
	v_mfma_f32_16x16x32_bf16 v[102:105], v[154:157], v[194:197], v[102:105]
	v_mfma_f32_16x16x32_bf16 v[94:97], v[162:165], v[194:197], v[94:97]
	v_mfma_f32_16x16x32_bf16 v[90:93], v[154:157], v[186:189], v[90:93]
	v_mfma_f32_16x16x32_bf16 v[86:89], v[162:165], v[186:189], v[86:89]
	s_setprio 0
	s_andn2_b64 s[40:41], exec, s[46:47]
	s_and_b64 vcc, exec, s[38:39]
	s_cbranch_vccnz .LBB0_1277
	s_and_b64 vcc, exec, s[40:41]
	s_cbranch_vccnz .LBB0_1274
	v_mfma_f32_16x16x32_bf16 v[18:21], v[174:177], v[6:9], v[18:21]
	v_mfma_f32_16x16x32_bf16 v[14:17], v[158:161], v[6:9], v[14:17]
	v_mfma_f32_16x16x32_bf16 v[18:21], v[178:181], v[10:13], v[18:21]
	v_mfma_f32_16x16x32_bf16 v[14:17], v[162:165], v[10:13], v[14:17]
	s_branch .LBB0_1277

; #define PG8_STAGE(bufoff, gbase, voff) do { _Pragma("unroll") for (int _i = 0; _i < 2; ++_i) glds16_s((voff)[_i], (const void*)(gbase), ldsbase + (unsigned)((bufoff) + _i * 8192) + ldsw); } while (0)
; #define PG8_LDA(dst, b, h) do { _Pragma("unroll") for (int m = 0; m < 4; ++m) _Pragma("unroll") for (int k = 0; k < 2; ++k) dst[m][k] = *(const PG8_LAS bf16x8*)(lds + PG8_SA(b, h) + aoff + m * 2048 + k * 1024); } while (0)
; #define PG8_LDB(dst, b, h) do { _Pragma("unroll") for (int n = 0; n < 2; ++n) _Pragma("unroll") for (int k = 0; k < 2; ++k) dst[n][k] = *(const PG8_LAS bf16x8*)(lds + PG8_SB(b, h) + boff + n * 2048 + k * 1024); } while (0)
; #define PG8_LDX(pb, tp) do { _Pragma("unroll") for (int k = 0; k < 2; ++k) Ax[k] = *(const PG8_LAS bf16x8*)(lds + xoff + (pb) * 4096 + (tp) * 128 + k * 64); } while (0)
; #define PG8_MMA(ai, bj, At, Bt) do { __builtin_amdgcn_s_setprio(1); _Pragma("unroll") for (int m = 0; m < 4; ++m) _Pragma("unroll") for (int n = 0; n < 2; ++n) _Pragma("unroll") for (int k = 0; k < 2; ++k) \
;         acc[ai][bj][m][n] = __builtin_amdgcn_mfma_f32_16x16x32_bf16(Bt[n][k], At[m][k], acc[ai][bj][m][n], 0, 0, 0); __builtin_amdgcn_s_setprio(0); } while (0)
; #define PG8_WAIT_V(n) asm volatile("s_waitcnt vmcnt(" #n ")" ::: "memory")
; #define PG8_WAIT_L(n) asm volatile("s_waitcnt lgkmcnt(" #n ")" ::: "memory")
; #define PG8_BAR __builtin_amdgcn_s_barrier()
; #define PG8_SCHED __builtin_amdgcn_sched_barrier(0)
; template <class Epi, class Sched, bool HM = false>
; __device__ __forceinline__ void gemm_phase(PG8_LAS unsigned char* lds, const Gemm g, const Sched& S, const Epi& E) {
;     ...
;             PG8_LDB(B0, 1, 0); PG8_LDB(B1, 1, 1); PG8_SCHED; PG8_LDA(At, 1, 0); if (hasx) PG8_LDX(pb, 1); PG8_STAGE(PG8_SA(0, 1), a2 + hstepA, voffA);
;             PG8_WAIT_V(9); PG8_WAIT_L(0); PG8_BAR; PG8_MMA(0, 0, At, B0); PG8_MMA(0, 1, At, B1); if (hasx) PG8_MMAX(); PG8_BAR; PG8_SCHED;
.LBB0_1279:
	s_add_u32 s8, s8, 0x160000
	s_addc_u32 s9, s9, 0
	s_mov_b32 s20, m0
	s_mov_b32 m0, s30
	s_nop 0
	global_load_lds_dwordx4 v225, s[8:9]
	s_mov_b32 m0, s20
	s_nop 0
	s_mov_b32 s20, m0
	s_mov_b32 m0, s31
	s_nop 0
	global_load_lds_dwordx4 v227, s[8:9]
	s_mov_b32 m0, s20
	s_waitcnt vmcnt(9)
	s_waitcnt lgkmcnt(0)
	s_barrier
	s_setprio 1
	s_waitcnt lgkmcnt(7)
	v_mfma_f32_16x16x32_bf16 v[146:149], v[166:169], v[206:209], v[146:149]
	v_mfma_f32_16x16x32_bf16 v[142:145], v[174:177], v[206:209], v[142:145]
	s_waitcnt lgkmcnt(5)
	v_mfma_f32_16x16x32_bf16 v[138:141], v[166:169], v[198:201], v[138:141]
	v_mfma_f32_16x16x32_bf16 v[130:133], v[174:177], v[198:201], v[130:133]
	s_waitcnt lgkmcnt(3)
	v_mfma_f32_16x16x32_bf16 v[122:125], v[166:169], v[190:193], v[122:125]
	v_mfma_f32_16x16x32_bf16 v[114:117], v[174:177], v[190:193], v[114:117]
	s_waitcnt lgkmcnt(1)
	v_mfma_f32_16x16x32_bf16 v[106:109], v[166:169], v[182:185], v[106:109]
	v_mfma_f32_16x16x32_bf16 v[98:101], v[174:177], v[182:185], v[98:101]
	v_mfma_f32_16x16x32_bf16 v[146:149], v[170:173], v[210:213], v[146:149]
	v_mfma_f32_16x16x32_bf16 v[142:145], v[178:181], v[210:213], v[142:145]
	v_mfma_f32_16x16x32_bf16 v[138:141], v[170:173], v[202:205], v[138:141]
	v_mfma_f32_16x16x32_bf16 v[130:133], v[178:181], v[202:205], v[130:133]
	v_mfma_f32_16x16x32_bf16 v[122:125], v[170:173], v[194:197], v[122:125]
	v_mfma_f32_16x16x32_bf16 v[114:117], v[178:181], v[194:197], v[114:117]
	s_waitcnt lgkmcnt(0)
	v_mfma_f32_16x16x32_bf16 v[106:109], v[170:173], v[186:189], v[106:109]
	v_mfma_f32_16x16x32_bf16 v[98:101], v[178:181], v[186:189], v[98:101]
	s_setprio 0
	s_setprio 1
	v_mfma_f32_16x16x32_bf16 v[134:137], v[150:153], v[206:209], v[134:137]
	v_mfma_f32_16x16x32_bf16 v[126:129], v[158:161], v[206:209], v[126:129]
	v_mfma_f32_16x16x32_bf16 v[118:121], v[150:153], v[198:201], v[118:121]
	v_mfma_f32_16x16x32_bf16 v[110:113], v[158:161], v[198:201], v[110:113]
	v_mfma_f32_16x16x32_bf16 v[102:105], v[150:153], v[190:193], v[102:105]
	v_mfma_f32_16x16x32_bf16 v[94:97], v[158:161], v[190:193], v[94:97]
	v_mfma_f32_16x16x32_bf16 v[90:93], v[150:153], v[182:185], v[90:93]
	v_mfma_f32_16x16x32_bf16 v[86:89], v[158:161], v[182:185], v[86:89]
	v_mfma_f32_16x16x32_bf16 v[134:137], v[154:157], v[210:213], v[134:137]
	v_mfma_f32_16x16x32_bf16 v[126:129], v[162:165], v[210:213], v[126:129]
	v_mfma_f32_16x16x32_bf16 v[118:121], v[154:157], v[202:205], v[118:121]
	v_mfma_f32_16x16x32_bf16 v[110:113], v[162:165], v[202:205], v[110:113]
	v_mfma_f32_16x16x32_bf16 v[102:105], v[154:157], v[194:197], v[102:105]
	v_mfma_f32_16x16x32_bf16 v[94:97], v[162:165], v[194:197], v[94:97]
	v_mfma_f32_16x16x32_bf16 v[90:93], v[154:157], v[186:189], v[90:93]
	v_mfma_f32_16x16x32_bf16 v[86:89], v[162:165], v[186:189], v[86:89]
	s_setprio 0
	s_and_b64 vcc, exec, s[38:39]
	s_cbranch_vccnz .LBB0_1268
	s_and_b64 vcc, exec, s[40:41]
	s_cbranch_vccnz .LBB0_1282
	v_mfma_f32_16x16x32_bf16 v[18:21], v[174:177], v[6:9], v[18:21]
	v_mfma_f32_16x16x32_bf16 v[14:17], v[158:161], v[6:9], v[14:17]
	v_mfma_f32_16x16x32_bf16 v[18:21], v[178:181], v[10:13], v[18:21]
	v_mfma_f32_16x16x32_bf16 v[14:17], v[162:165], v[10:13], v[14:17]
	s_branch .LBB0_1267
